# v82 + P3: workgroups with bit 4 of their id set run the two sample-attention units before the twelve prompt-attention units (HBM-bound and compute-bound work overlap across workgroups)
# baseline (speedup 1.0000x reference)
; #define ATTN_UNIT_OF(i, U) { const int v_ = xa ? sl + 32 * (i) : bid + G * (i), rest_ = v_ % 48; U = attn_decode(xa ? x + 8 * (v_ / 48) : v_ / 48, rest_ >> 4, rest_ & 15); }
; __device__ __forceinline__ void phase3(const Params& p, unsigned char* lds, int bid, int G) {
;     {
;         const bool xa = (G == 256);
;         const int x = bid & 7, sl = bid >> 3;
;         const int nun = xa ? 12 : (3072 - bid + G - 1) / G;
;     ...
;         for (int i = 0; i < nun; ++i) {
;             AttnUnit uc; ATTN_UNIT_OF(i, uc);
;             bf16x8 qf[4]; attn_qload(p, uc, qf);
;             { uint4 sk_[6], sv_[6]; attn_stage_load(p, uc, sk_, sv_); attn_stage_store(sk_, sv_, lds); }
;             __syncthreads();
;             attn_compute(p, uc, lds, qf);
;             __syncthreads();
;         }
;     ...
;     }
;     for (int u = bid; u < 512; u += G) attn_sample_unit(p, u, (float*)lds);
.LBB0_333:
	s_cmp_lt_i32 s3, 1
	v_lshrrev_b32_e32 v177, 1, v172
	v_lshl_add_u32 v78, v175, 4, 0
	v_lshlrev_b32_e32 v180, 2, v175
	v_lshlrev_b32_e32 v195, 3, v175
	s_mov_b32 s94, 0
	s_bitcmp1_b32 s2, 4
	s_cbranch_scc0 .Lp3_order_ab
	s_mov_b32 s94, 1
	s_mov_b32 s95, s3
	s_mov_b64 s[96:97], s[12:13]
	s_branch .LBB0_344

; __device__ __forceinline__ void attn_stage_load(const Params& p, const AttnUnit u, uint4 (&sk)[6], uint4 (&sv)[6]) {
;     const int h = u.bh & 15, b = u.bh >> 4, tid = threadIdx.x;
;     const int dsh = 2 * u.br, nsub = 4096 >> dsh, k_lo = u.i_start - 128;
;     const bfu* vt = (const bfu*)(p.ws + WS_VT) + (size_t)u.br * VT_SZ + (size_t)u.bh * 64 * 4096 + u.r * nsub;
;     const bfu* kbase = (const bfu*)(p.ws + WS_PROJ) + (size_t)(b * 4096 + u.r) * NPROJ + 1024 + h * 64;
; #pragma unroll
;     for (int i = 0; i < 6; ++i) {
;         const int e = tid + 512 * i;
;         { const int key = e >> 3, c = e & 7; int ik = k_lo + key; ik = ik < 0 ? 0 : ik; sk[i] = *(const uint4*)(kbase + ((size_t)ik << dsh) * NPROJ + c * 8); }
;         { const int d = e / 48, c = e - d * 48; int ik = k_lo + c * 8; ik = ik < 0 ? 0 : ik; sv[i] = *(const uint4*)(vt + (size_t)d * 4096 + ik); }
;     }
; }
; __device__ __forceinline__ void attn_stage_store(const uint4 (&sk)[6], const uint4 (&sv)[6], unsigned char* ldsb) {
;     bfu* Kl = (bfu*)ldsb; bfu* Vl = Kl + 384 * 72; const int tid = threadIdx.x;
; #pragma unroll
;     for (int i = 0; i < 6; ++i) {
;         const int e = tid + 512 * i;
;         { const int key = e >> 3, c = e & 7; *(uint4*)(Kl + key * 72 + c * 8) = sk[i]; }
;         { const int d = e / 48, c = e - d * 48; *(uint4*)(Vl + d * 392 + c * 8) = sv[i]; }
;     }
; }
; __device__ __forceinline__ void attn_compute(const Params& p, const AttnUnit u, unsigned char* ldsb, const bf16x8 (&qf)[4]) {
;     ...
;         const int dbase = 128 + l15 - quad * 4;
;         const int dmax = (i0 + l15) < 128 ? (i0 + l15) : 128;
;         const float sd = slope * (float)(1 << dsh) * 1.4426950408889634f, nb = -sd * (float)dbase;
;         float mx = NINF;
; #pragma unroll
;         for (int kt = 0; kt < 9; ++kt)
; #pragma unroll
;             for (int j = 0; j < 4; ++j) {
;                 const int cst = 16 * kt + j;
;                 const float bias = __builtin_fmaf(sd, (float)cst, nb);
;                 float v = __builtin_fmaf(s[kt][j], 0.125f * 1.4426950408889634f, bias);
;                 if (kt == 0 || kt == 8 || i_start == 0) v = ((unsigned)(dbase - cst) <= (unsigned)dmax) ? v : NINF;
.Lp3_a_entry:
	s_cbranch_scc1 .LBB0_344
	v_or_b32_e32 v14, 0x800, v172
	v_mul_u32_u24_e32 v16, 0xaab, v14
	v_add_u32_e32 v5, 0x200, v172
	v_or_b32_e32 v9, 0x400, v172
	v_add_u32_e32 v12, 0x600, v172
	v_lshrrev_b32_e32 v17, 17, v16
	v_add_u32_e32 v16, 0xa00, v172
	v_mul_u32_u24_e32 v1, 0x556, v172
	v_mul_u32_u24_e32 v7, 0x556, v5
	v_mul_u32_u24_e32 v10, 0x556, v9
	v_mul_u32_u24_e32 v13, 0xaab, v12
	v_mul_u32_u24_e32 v19, 0xaab, v16
	v_lshrrev_b32_e32 v1, 16, v1
	s_movk_i32 s0, 0xffd0
	v_lshrrev_b32_e32 v7, 16, v7
	v_lshrrev_b32_e32 v11, 16, v10
	v_lshrrev_b32_e32 v13, 17, v13
	v_lshrrev_b32_e32 v19, 17, v19
	v_mad_i32_i24 v3, v1, s0, v172
	v_lshrrev_b32_e32 v41, 3, v5
	v_mad_i32_i24 v5, v7, s0, v5
	v_lshrrev_b32_e32 v43, 3, v9
	v_mad_i32_i24 v9, v11, s0, v9
	v_mad_i32_i24 v15, v13, s0, v12
	v_mad_i32_i24 v18, v17, s0, v14
	v_mad_i32_i24 v20, v19, s0, v16
	s_movk_i32 s0, 0x310
	v_lshlrev_b32_e32 v40, 3, v3
	v_lshlrev_b32_e32 v6, 12, v1
	v_mad_u32_u24 v1, v1, s0, 0
	v_lshlrev_b32_e32 v3, 4, v3
	s_mov_b32 s4, 0xd800
	v_add3_u32 v52, v1, v3, s4
	v_mad_u32_u24 v1, v7, s0, 0
	v_lshlrev_b32_e32 v3, 4, v5
	v_add3_u32 v54, v1, v3, s4
	v_mad_u32_u24 v1, v11, s0, 0
	v_lshlrev_b32_e32 v3, 4, v9
	v_add3_u32 v56, v1, v3, s4
	v_mad_u32_u24 v1, v13, s0, 0
	v_lshlrev_b32_e32 v3, 4, v15
	v_add3_u32 v58, v1, v3, s4
	v_mad_u32_u24 v1, v17, s0, 0
	v_lshlrev_b32_e32 v3, 4, v18
	v_add3_u32 v60, v1, v3, s4
	v_mad_u32_u24 v1, v19, s0, 0
	v_lshlrev_b32_e32 v3, 4, v20
	v_add3_u32 v62, v1, v3, s4
	v_mbcnt_lo_u32_b32 v1, -1, 0
	s_load_dwordx2 s[4:5], s[42:43], 0xb8
	v_mbcnt_hi_u32_b32 v1, -1, v1
	v_lshlrev_b32_e32 v42, 3, v5
	v_and_b32_e32 v5, 64, v1
	v_xor_b32_e32 v3, 16, v1
	v_add_u32_e32 v5, 64, v5
	s_and_b32 s22, s2, 7
	s_ashr_i32 s23, s2, 3
	v_cmp_lt_i32_e32 vcc, v3, v5
	s_waitcnt lgkmcnt(0)
	s_add_u32 s8, s4, 0x4300000
	s_addc_u32 s9, s5, 0
	v_cndmask_b32_e32 v3, v1, v3, vcc
	v_lshlrev_b32_e32 v66, 2, v3
	v_xor_b32_e32 v3, 32, v1
	v_cmp_lt_i32_e32 vcc, v3, v5
	s_add_u32 s25, s4, 0x10600000
	s_addc_u32 s26, s5, 0
	v_cndmask_b32_e32 v1, v1, v3, vcc
	v_lshlrev_b32_e32 v67, 2, v1
	v_mov_b32_e32 v1, 0x3100
	s_add_u32 s27, s4, 0x28d00000
	v_and_b32_e32 v4, 56, v181
	v_or_b32_e32 v63, 0x80, v174
	v_mad_u32_u24 v107, v174, s0, v1
	v_mov_b32_e32 v1, 0x6200
	s_addc_u32 s28, s5, 0
	v_and_b32_e32 v0, 24, v177
	v_lshlrev_b32_e32 v8, 12, v7
	v_lshlrev_b32_e32 v10, 12, v11
	v_lshrrev_b32_e32 v45, 3, v12
	v_lshlrev_b32_e32 v12, 12, v13
	v_lshrrev_b32_e32 v47, 3, v14
	v_lshlrev_b32_e32 v14, 12, v17
	v_lshrrev_b32_e32 v49, 3, v16
	v_lshlrev_b32_e32 v16, 12, v19
	v_lshl_add_u32 v21, v4, 1, 0
	s_movk_i32 s24, 0x90
	v_sub_u32_e32 v64, v63, v180
	v_mad_u32_u24 v108, v174, s0, v1
	v_mov_b32_e32 v1, 0x9300
	s_add_u32 s29, s4, 0x30f00000
	v_mov_b32_e32 v2, 0
	v_lshlrev_b32_e32 v44, 3, v9
	v_lshlrev_b32_e32 v46, 3, v15
	v_lshlrev_b32_e32 v48, 3, v18
	v_lshlrev_b32_e32 v50, 3, v20
	s_mov_b32 s1, 0
	v_mad_u32_u24 v51, v76, s24, v21
	v_mad_u32_u24 v53, v41, s24, v21
	v_mad_u32_u24 v55, v43, s24, v21
	v_mad_u32_u24 v57, v45, s24, v21
	v_mad_u32_u24 v59, v47, s24, v21
	v_mad_u32_u24 v61, v49, s24, v21
	v_cvt_f32_ubyte0_e32 v65, v64
	v_sub_u32_e32 v68, v78, v195
	v_cmp_eq_u32_e64 s[6:7], 0, v175
	v_add_u32_e32 v69, -1, v64
	v_add_u32_e32 v70, -2, v64
	v_add_u32_e32 v71, -3, v64
	v_add_u32_e32 v72, -16, v64
	v_subrev_u32_e32 v73, 17, v64
	v_subrev_u32_e32 v74, 18, v64
	v_subrev_u32_e32 v75, 19, v64
	v_subrev_u32_e32 v77, 32, v64
	v_subrev_u32_e32 v79, 33, v64
	v_subrev_u32_e32 v80, 34, v64
	v_subrev_u32_e32 v81, 35, v64
	v_subrev_u32_e32 v82, 48, v64
	v_subrev_u32_e32 v83, 49, v64
	v_subrev_u32_e32 v84, 50, v64
	v_subrev_u32_e32 v85, 51, v64
	v_subrev_u32_e32 v86, 64, v64
	v_add_u32_e32 v87, 0xffffffbf, v64
	v_add_u32_e32 v88, 0xffffffbe, v64
	v_add_u32_e32 v89, 0xffffffbd, v64
	v_add_u32_e32 v90, 0xffffffb0, v64
	v_add_u32_e32 v91, 0xffffffaf, v64
	v_add_u32_e32 v92, 0xffffffae, v64
	v_add_u32_e32 v93, 0xffffffad, v64
	v_add_u32_e32 v94, 0xffffffa0, v64
	v_add_u32_e32 v95, 0xffffff9f, v64
	v_add_u32_e32 v96, 0xffffff9e, v64
	v_add_u32_e32 v97, 0xffffff9d, v64
	v_add_u32_e32 v98, 0xffffff90, v64
	v_add_u32_e32 v99, 0xffffff8f, v64
	v_add_u32_e32 v100, 0xffffff8e, v64
	v_add_u32_e32 v101, 0xffffff8d, v64
	v_add_u32_e32 v102, 0xffffff80, v64
	v_add_u32_e32 v103, 0xffffff7f, v64
	v_add_u32_e32 v104, 0xffffff7e, v64
	v_add_u32_e32 v105, 0xffffff7d, v64
	v_mul_u32_u24_e32 v106, 0x310, v174
	v_mad_u32_u24 v109, v174, s0, v1
	v_or_b32_e32 v110, 16, v174
	v_or_b32_e32 v111, 32, v174
	v_or_b32_e32 v112, 48, v174
	v_or_b32_e32 v113, 64, v174
	v_or_b32_e32 v114, 0x50, v174
	v_or_b32_e32 v115, 0x60, v174
	v_or_b32_e32 v116, 0x70, v174
	s_addc_u32 s30, s5, 0
	s_movk_i32 s31, 0x3000
	v_lshlrev_b32_e32 v20, 1, v0
	v_lshlrev_b32_e32 v22, 1, v4
	s_mov_b64 s[10:11], 0x4300800
	v_lshlrev_b32_e32 v24, 1, v6
	v_lshlrev_b32_e32 v26, 1, v8
	v_lshlrev_b32_e32 v28, 1, v10
	v_lshlrev_b32_e32 v30, 1, v12
	v_lshlrev_b32_e32 v32, 1, v14
	v_lshlrev_b32_e32 v34, 1, v16
	s_mov_b32 s33, 0xc2fc0000
	v_lshlrev_b32_e32 v36, 1, v180
	s_mov_b32 s34, 0xff800000
	v_mov_b32_e32 v117, 0x42800000
	v_mov_b32_e32 v118, 0xff800000
	s_mov_b32 s35, 0
	s_branch .LBB0_336

; __device__ __forceinline__ float bflo(unsigned u) { return __uint_as_float(u << 16); }
; __device__ __forceinline__ float bfhi(unsigned u) { return __uint_as_float(u & 0xffff0000u); }
; __device__ __forceinline__ void attn_sample_unit(const Params& p, int unit, float* lds) {
;     const int h = unit & 15, b = unit >> 4;
;     const int tid = threadIdx.x, lane = tid & 63, wave = tid >> 6, ks = lane >> 4, d4 = lane & 15;
;     float* sbuf = lds + wave * 136;
;     const int row = MP + b * 8 + wave;
;     const bfu* proj = (const bfu*)(p.ws + WS_PROJ);
;     const uint2 qu = *(const uint2*)(proj + (size_t)row * NPROJ + h * 64 + d4 * 4);
;     const float q0 = bflo(qu.x) * 0.125f, q1 = bfhi(qu.x) * 0.125f, q2 = bflo(qu.y) * 0.125f, q3 = bfhi(qu.y) * 0.125f;
;     const float slope = exp2f(-0.5f * (float)(h + 1));
;     const float* kc = p.cache_k + ((size_t)b * 2048 * 16 + h) * 64 + d4 * 4;
;     const float* vc = p.cache_v + ((size_t)b * 2048 * 16 + h) * 64 + d4 * 4;
;     const float* kn = p.out + O_KS + ((size_t)b * 8 * 16 + h) * 64 + d4 * 4;
;     const float* vn = p.out + O_VS + ((size_t)b * 8 * 16 + h) * 64 + d4 * 4;
;     const float NINF = -__builtin_inff();
;     float mr = NINF, lr = 0.f; float4 orun = make_float4(0.f, 0.f, 0.f, 0.f);
.LBB0_344:
	s_cmpk_lt_i32 s2, 0x200
	s_cselect_b64 s[0:1], -1, 0
	s_cmpk_gt_i32 s2, 0x1ff
	v_and_b32_e32 v179, 63, v172
	s_cbranch_scc1 .LBB0_370
	s_cmp_eq_u32 s94, 2
	s_cbranch_scc1 .LBB0_370
	v_mbcnt_lo_u32_b32 v1, -1, 0
	v_mbcnt_hi_u32_b32 v1, -1, v1
	v_and_b32_e32 v3, 64, v1
	v_xor_b32_e32 v2, 32, v1
	v_add_u32_e32 v3, 64, v3
	v_cmp_lt_i32_e32 vcc, v2, v3
	s_load_dwordx4 s[12:15], s[42:43], 0xb0
	s_load_dwordx4 s[16:19], s[42:43], 0x10
	v_cndmask_b32_e32 v2, v1, v2, vcc
	v_lshlrev_b32_e32 v126, 2, v2
	v_xor_b32_e32 v2, 16, v1
	v_cmp_lt_i32_e32 vcc, v2, v3
	v_mov_b32_e32 v69, 0
	v_lshlrev_b32_e32 v68, 4, v174
	v_cndmask_b32_e32 v2, v1, v2, vcc
	v_lshlrev_b32_e32 v127, 2, v2
	v_xor_b32_e32 v2, 8, v1
	v_cmp_lt_i32_e32 vcc, v2, v3
	s_waitcnt lgkmcnt(0)
	s_add_u32 s20, s14, 0x4300000
	s_movk_i32 s3, 0x220
	v_cndmask_b32_e32 v2, v1, v2, vcc
	v_lshlrev_b32_e32 v128, 2, v2
	v_xor_b32_e32 v2, 4, v1
	v_cmp_lt_i32_e32 vcc, v2, v3
	v_lshlrev_b32_e32 v0, 2, v174
	s_addc_u32 s21, s15, 0
	v_cndmask_b32_e32 v2, v1, v2, vcc
	v_lshlrev_b32_e32 v129, 2, v2
	v_xor_b32_e32 v2, 2, v1
	v_cmp_lt_i32_e32 vcc, v2, v3
	v_mad_u32_u24 v77, v194, s3, 0
	v_lshlrev_b32_e32 v84, 1, v0
	v_cndmask_b32_e32 v2, v1, v2, vcc
	v_lshlrev_b32_e32 v130, 2, v2
	v_xor_b32_e32 v2, 1, v1
	v_cmp_lt_i32_e32 vcc, v2, v3
	s_mov_b32 s5, 0
	v_or_b32_e32 v79, 0x4000, v194
	v_cndmask_b32_e32 v1, v1, v2, vcc
	v_lshl_add_u64 v[2:3], s[12:13], 0, v[68:69]
	s_mov_b64 s[12:13], 0x8318000
	v_lshl_add_u64 v[74:75], v[2:3], 0, s[12:13]
	s_mov_b64 s[12:13], 0x8418000
	v_lshl_add_u64 v[80:81], v[2:3], 0, s[12:13]
	s_add_u32 s12, s14, 0x1a900000
	s_movk_i32 s3, 0x800
	v_or_b32_e32 v111, 0x800, v194
	v_cmp_eq_u32_e64 s[6:7], 0, v174
	v_lshl_add_u32 v113, v179, 2, v77
	v_cmp_eq_u32_e64 s[8:9], 0, v179
	v_lshlrev_b32_e32 v131, 2, v1
	v_or_b32_e32 v132, 4, v175
	v_or_b32_e32 v133, 12, v175
	v_or_b32_e32 v134, 20, v175
	v_or_b32_e32 v135, 28, v175
	v_or_b32_e32 v136, 36, v175
	v_or_b32_e32 v137, 44, v175
	v_or_b32_e32 v138, 52, v175
	v_or_b32_e32 v139, 60, v175
	v_or_b32_e32 v140, 64, v175
	v_cmp_gt_u32_e64 s[10:11], 16, v179
	v_lshl_add_u64 v[70:71], s[16:17], 0, v[68:69]
	v_lshl_add_u64 v[72:73], s[18:19], 0, v[68:69]
	s_addc_u32 s13, s15, 0
	s_movk_i32 s18, 0x3000
	v_mov_b64_e32 v[82:83], s[20:21]
	v_mov_b32_e32 v86, v84
	v_mov_b32_e32 v87, v69
	s_mov_b32 s19, 0xc2fc0000
	v_mov_b32_e32 v141, 0x42800000
	s_movk_i32 s20, 0x81
	s_mov_b32 s21, s2
	s_branch .LBB0_347

; __device__ __forceinline__ void phase3(const Params& p, unsigned char* lds, int bid, int G) {
;     ...
;     for (int u = bid; u < 512; u += G) attn_sample_unit(p, u, (float*)lds);
;     __syncthreads();
;     for (int u = bid; u < 512; u += G) ssd_s1_unit(p, u, lds);
;     for (int u = bid; u < 512; u += G) ssd_sample_unit(p, u, (float*)lds);
.LBB0_370:
	s_cmp_eq_u32 s94, 1
	s_cbranch_scc0 .Lp3_no_a
	s_mov_b32 s94, 2
	s_mov_b32 s3, s95
	s_mov_b64 s[12:13], s[96:97]
	s_barrier
	s_cmp_lt_i32 s3, 1
	s_branch .Lp3_a_entry
